# hg_sequence: next-chunk prefetch loads and per-step stores use saddr form (SGPR base from rotating readlane pairs + 32-bit lane offset), removing 33 v_lshl_add_u64 per chunk
# baseline (speedup 1.0000x reference)
.LBB0_1410:
	s_waitcnt vmcnt(38)
	v_lshlrev_b32_e32 v101, 16, v16
	v_sub_f32_e32 v128, 1.0, v101
	v_max_f32_e32 v128, 0x3a800000, v128
	s_mov_b32 s2, 0x800000
	s_mov_b32 s3, 0x3f317217
	s_mov_b32 s28, 0x7f800000
	v_log_f32_e32 v128, v128
	v_and_b32_e32 v104, 0xffff0000, v16
	s_waitcnt vmcnt(36)
	v_lshlrev_b32_e32 v102, 16, v17
	v_and_b32_e32 v105, 0xffff0000, v17
	v_mul_f32_e32 v58, 0x3f317217, v128
	v_fma_f32 v58, v128, s3, -v58
	v_fmac_f32_e32 v58, 0x3377d1cf, v128
	v_fmac_f32_e32 v58, 0x3f317217, v128
	s_waitcnt vmcnt(32)
	v_lshlrev_b32_e32 v103, 16, v18
	v_and_b32_e32 v107, 0xffff0000, v18


	v_sub_f32_e32 v129, 1.0, v104
	v_max_f32_e32 v129, 0x3a800000, v129
	s_waitcnt vmcnt(30)
	v_lshlrev_b32_e32 v106, 16, v19
	v_and_b32_e32 v109, 0xffff0000, v19
	v_log_f32_e32 v129, v129
	s_waitcnt vmcnt(26)
	v_lshlrev_b32_e32 v108, 16, v20
	v_and_b32_e32 v112, 0xffff0000, v20
	s_waitcnt vmcnt(24)
	v_lshlrev_b32_e32 v110, 16, v21
	v_mul_f32_e32 v59, 0x3f317217, v129
	v_fma_f32 v59, v129, s3, -v59
	v_fmac_f32_e32 v59, 0x3377d1cf, v129
	v_fmac_f32_e32 v59, 0x3f317217, v129
	v_and_b32_e32 v114, 0xffff0000, v21
	s_waitcnt vmcnt(19)
	v_lshlrev_b32_e32 v113, 16, v22


	v_pk_add_f32 v[62:63], v[58:59], 0 op_sel_hi:[1,0]
	v_sub_f32_e32 v130, 1.0, v102
	v_max_f32_e32 v130, 0x3a800000, v130
	v_and_b32_e32 v116, 0xffff0000, v22
	s_waitcnt vmcnt(18)
	v_lshlrev_b32_e32 v115, 16, v23
	v_log_f32_e32 v130, v130
	v_and_b32_e32 v117, 0xffff0000, v23
	v_mov_b32_e32 v99, v83
	v_mov_b32_e32 v0, v82
	v_mul_f32_e32 v58, 0x3f317217, v130
	v_fma_f32 v58, v130, s3, -v58
	v_fmac_f32_e32 v58, 0x3377d1cf, v130
	v_fmac_f32_e32 v58, 0x3f317217, v130
	v_mov_b32_e32 v100, v98


	v_sub_f32_e32 v131, 1.0, v105
	v_max_f32_e32 v131, 0x3a800000, v131

	v_log_f32_e32 v131, v131
	s_nop 0
	v_mul_f32_e32 v59, 0x3f317217, v131
	v_fma_f32 v59, v131, s3, -v59
	v_fmac_f32_e32 v59, 0x3377d1cf, v131
	v_fmac_f32_e32 v59, 0x3f317217, v131


	v_sub_f32_e32 v132, 1.0, v103
	v_max_f32_e32 v132, 0x3a800000, v132
	v_pk_add_f32 v[58:59], v[58:59], v[62:63]

	v_log_f32_e32 v132, v132
	s_nop 0
	v_mul_f32_e32 v60, 0x3f317217, v132
	v_fma_f32 v60, v132, s3, -v60
	v_fmac_f32_e32 v60, 0x3377d1cf, v132
	v_fmac_f32_e32 v60, 0x3f317217, v132


	v_sub_f32_e32 v133, 1.0, v107
	v_max_f32_e32 v133, 0x3a800000, v133

	v_log_f32_e32 v133, v133
	s_nop 0
	v_mul_f32_e32 v61, 0x3f317217, v133
	v_fma_f32 v61, v133, s3, -v61
	v_fmac_f32_e32 v61, 0x3377d1cf, v133
	v_fmac_f32_e32 v61, 0x3f317217, v133
	s_nop 1


	v_sub_f32_e32 v134, 1.0, v106
	v_max_f32_e32 v134, 0x3a800000, v134
	v_pk_add_f32 v[60:61], v[60:61], v[58:59]

	v_log_f32_e32 v134, v134
	s_nop 0
	v_mul_f32_e32 v64, 0x3f317217, v134
	v_fma_f32 v64, v134, s3, -v64
	v_fmac_f32_e32 v64, 0x3377d1cf, v134
	v_fmac_f32_e32 v64, 0x3f317217, v134
	s_nop 1


	v_sub_f32_e32 v135, 1.0, v109
	v_max_f32_e32 v135, 0x3a800000, v135

	v_log_f32_e32 v135, v135
	s_nop 0
	v_mul_f32_e32 v65, 0x3f317217, v135
	v_fma_f32 v65, v135, s3, -v65
	v_fmac_f32_e32 v65, 0x3377d1cf, v135
	v_fmac_f32_e32 v65, 0x3f317217, v135
	s_nop 1


	v_pk_add_f32 v[66:67], v[64:65], v[60:61]
	v_sub_f32_e32 v136, 1.0, v108
	v_max_f32_e32 v136, 0x3a800000, v136

	v_log_f32_e32 v136, v136
	s_nop 0
	v_mul_f32_e32 v64, 0x3f317217, v136
	v_fma_f32 v64, v136, s3, -v64
	v_fmac_f32_e32 v64, 0x3377d1cf, v136
	v_fmac_f32_e32 v64, 0x3f317217, v136
	s_nop 1


	v_sub_f32_e32 v137, 1.0, v112
	v_max_f32_e32 v137, 0x3a800000, v137

	v_log_f32_e32 v137, v137
	s_nop 0
	v_mul_f32_e32 v65, 0x3f317217, v137
	v_fma_f32 v65, v137, s3, -v65
	v_fmac_f32_e32 v65, 0x3377d1cf, v137
	v_fmac_f32_e32 v65, 0x3f317217, v137
	s_nop 1


	v_pk_add_f32 v[68:69], v[64:65], v[66:67]
	v_sub_f32_e32 v138, 1.0, v110
	v_max_f32_e32 v138, 0x3a800000, v138

	v_log_f32_e32 v138, v138
	s_nop 0
	v_mul_f32_e32 v64, 0x3f317217, v138
	v_fma_f32 v64, v138, s3, -v64
	v_fmac_f32_e32 v64, 0x3377d1cf, v138
	v_fmac_f32_e32 v64, 0x3f317217, v138
	s_nop 1


	v_sub_f32_e32 v139, 1.0, v114
	v_max_f32_e32 v139, 0x3a800000, v139

	v_log_f32_e32 v139, v139
	s_nop 0
	v_mul_f32_e32 v65, 0x3f317217, v139
	v_fma_f32 v65, v139, s3, -v65
	v_fmac_f32_e32 v65, 0x3377d1cf, v139
	v_fmac_f32_e32 v65, 0x3f317217, v139
	s_nop 1


	v_pk_add_f32 v[70:71], v[64:65], v[68:69]
	v_sub_f32_e32 v140, 1.0, v113
	v_max_f32_e32 v140, 0x3a800000, v140

	v_log_f32_e32 v140, v140
	s_nop 0
	v_mul_f32_e32 v64, 0x3f317217, v140
	v_fma_f32 v64, v140, s3, -v64
	v_fmac_f32_e32 v64, 0x3377d1cf, v140
	v_fmac_f32_e32 v64, 0x3f317217, v140
	s_nop 1


	v_sub_f32_e32 v141, 1.0, v116
	v_max_f32_e32 v141, 0x3a800000, v141

	v_log_f32_e32 v141, v141
	s_nop 0
	v_mul_f32_e32 v65, 0x3f317217, v141
	v_fma_f32 v65, v141, s3, -v65
	v_fmac_f32_e32 v65, 0x3377d1cf, v141
	v_fmac_f32_e32 v65, 0x3f317217, v141
	s_nop 1


	v_pk_add_f32 v[72:73], v[64:65], v[70:71]
	v_sub_f32_e32 v142, 1.0, v115
	v_max_f32_e32 v142, 0x3a800000, v142

	v_log_f32_e32 v142, v142
	s_nop 0
	v_mul_f32_e32 v64, 0x3f317217, v142
	v_fma_f32 v64, v142, s3, -v64
	v_fmac_f32_e32 v64, 0x3377d1cf, v142
	v_fmac_f32_e32 v64, 0x3f317217, v142
	s_nop 1


	v_sub_f32_e32 v143, 1.0, v117
	v_max_f32_e32 v143, 0x3a800000, v143

	v_log_f32_e32 v143, v143
	s_nop 0
	v_mul_f32_e32 v65, 0x3f317217, v143
	v_fma_f32 v65, v143, s3, -v65
	v_fmac_f32_e32 v65, 0x3377d1cf, v143
	v_fmac_f32_e32 v65, 0x3f317217, v143
	s_nop 1


	v_pk_add_f32 v[74:75], v[64:65], v[72:73]
	v_lshlrev_b32_e32 v64, 2, v0
	v_add_u32_e32 v65, s76, v64
	ds_write_b64 v65, v[74:75]
	s_waitcnt lgkmcnt(0)
	s_barrier
	v_add_u32_e32 v111, 0, v64
	ds_read2st64_b64 v[76:79], v111 offset1:1
	ds_read2st64_b64 v[128:131], v111 offset0:2 offset1:3
	ds_read2st64_b64 v[132:135], v111 offset0:4 offset1:5
	ds_read2st64_b64 v[136:139], v111 offset0:6 offset1:7
	s_andn2_b64 vcc, exec, s[58:59]
	s_waitcnt lgkmcnt(3)
	v_pk_add_f32 v[64:65], v[76:77], 0 op_sel_hi:[1,0]
	s_nop 0
	v_pk_add_f32 v[80:81], v[64:65], v[78:79]
	v_cndmask_b32_e64 v86, 0, v65, s[10:11]
	v_cndmask_b32_e64 v87, 0, v64, s[10:11]
	s_waitcnt lgkmcnt(2)
	v_pk_add_f32 v[64:65], v[80:81], v[128:129]
	v_cndmask_b32_e64 v76, v87, v80, s[12:13]
	v_cndmask_b32_e64 v77, v86, v81, s[12:13]
	v_cndmask_b32_e64 v86, v77, v65, s[14:15]
	v_cndmask_b32_e64 v87, v76, v64, s[14:15]
	v_pk_add_f32 v[94:95], v[64:65], v[130:131]
	s_waitcnt lgkmcnt(1)
	v_pk_add_f32 v[64:65], v[94:95], v[132:133]
	v_cndmask_b32_e64 v76, v87, v94, s[16:17]
	v_cndmask_b32_e64 v77, v86, v95, s[16:17]
	v_cndmask_b32_e64 v77, v77, v65, s[18:19]
	v_cndmask_b32_e64 v76, v76, v64, s[18:19]
	v_pk_add_f32 v[96:97], v[64:65], v[134:135]
	s_nop 0
	v_cndmask_b32_e64 v88, v76, v96, s[20:21]
	v_cndmask_b32_e64 v89, v77, v97, s[20:21]
	s_waitcnt lgkmcnt(0)
	v_pk_add_f32 v[86:87], v[96:97], v[136:137]
	s_nop 0
	v_pk_add_f32 v[64:65], v[86:87], v[138:139]
	v_cndmask_b32_e64 v76, 0, v81, s[8:9]
	v_cndmask_b32_e64 v77, 0, v80, s[8:9]
	v_cndmask_b32_e64 v78, v81, v95, s[8:9]
	v_cndmask_b32_e64 v79, v80, v94, s[8:9]
	v_cndmask_b32_e64 v77, v77, v94, s[6:7]
	v_cndmask_b32_e64 v76, v76, v95, s[6:7]
	v_cndmask_b32_e64 v79, v79, v96, s[6:7]
	v_cndmask_b32_e64 v78, v78, v97, s[6:7]
	v_cndmask_b32_e64 v91, v76, v97, s[24:25]
	v_cndmask_b32_e64 v90, v77, v96, s[24:25]
	v_cndmask_b32_e64 v77, v78, v65, s[24:25]
	v_cndmask_b32_e64 v76, v79, v64, s[24:25]
	v_pk_add_f32 v[78:79], v[80:81], v[76:77] neg_lo:[0,1] neg_hi:[0,1]
	v_mul_f32_e32 v92, 0x3fb8aa3b, v90
	v_min_f32_e32 v78, 0, v78
	v_mul_f32_e32 v78, 0x3fb8aa3b, v78
	v_exp_f32_e32 v118, v78
	v_min_f32_e32 v78, 0, v79
	v_mul_f32_e32 v78, 0x3fb8aa3b, v78
	v_exp_f32_e32 v119, v78
	v_cndmask_b32_e64 v79, v89, v87, s[22:23]
	v_cndmask_b32_e64 v78, v88, v86, s[22:23]
	v_pk_add_f32 v[88:89], v[78:79], v[90:91] neg_lo:[0,1] neg_hi:[0,1]
	v_mul_f32_e32 v93, 0x3fb8aa3b, v91
	v_pk_add_f32 v[62:63], v[62:63], v[88:89]
	v_pk_add_f32 v[86:87], v[76:77], v[90:91] neg_lo:[0,1] neg_hi:[0,1]
	v_mul_f32_e32 v90, 0x3fb8aa3b, v62
	v_exp_f32_e32 v78, v93
	v_exp_f32_e32 v93, v90
	v_mul_f32_e32 v90, 0x3fb8aa3b, v63
	v_exp_f32_e32 v123, v90
	v_mul_f32_e32 v79, 0x3fb8aa3b, v84
	v_rcp_f32_e32 v90, v93
	v_exp_f32_e32 v80, v92
	v_exp_f32_e32 v92, v79
	v_mul_f32_e32 v79, 0x3fb8aa3b, v85
	v_exp_f32_e32 v122, v79
	v_min_f32_e32 v121, 0x79297b5a, v90
	v_rcp_f32_e32 v90, v123
	v_pk_add_f32 v[62:63], v[86:87], v[62:63] neg_lo:[0,1] neg_hi:[0,1]
	v_lshlrev_b32_e32 v79, 1, v0
	v_mul_f32_e32 v62, 0x3fb8aa3b, v62
	v_sub_u32_e32 v120, v111, v79
	v_lshlrev_b32_e32 v81, 16, v8
	v_and_b32_e32 v79, 0xffff0000, v8
	v_exp_f32_e32 v125, v62
	v_mul_f32_e32 v62, 0x3fb8aa3b, v63
	v_min_f32_e32 v124, 0x79297b5a, v90
	v_exp_f32_e32 v126, v62
	v_pk_mul_f32 v[90:91], v[92:93], v[80:81]
	v_pk_mul_f32 v[92:93], v[122:123], v[78:79]
	v_lshl_add_u32 v63, s39, 1, v120
	v_cvt_pk_bf16_f32 v62, v91, v93
	ds_write_b32 v63, v62 offset:8192
	v_mul_f32_e32 v62, v80, v91
	v_mul_f32_e32 v79, v78, v93
	v_cvt_pk_bf16_f32 v62, v62, v79
	ds_write_b32 v63, v62 offset:25600
	v_mul_f32_e32 v62, v90, v91
	v_mul_f32_e32 v63, v92, v93
	v_cvt_pk_bf16_f32 v79, v62, v63
	v_lshl_add_u64 v[62:63], v[0:1], 1, s[34:35]

	v_mul_f32_e32 v91, v121, v101
	v_mul_f32_e32 v93, v124, v104
	global_store_dword v62, v79, s[52:53]
	v_cvt_pk_bf16_f32 v91, v91, v93
	v_add_u32_e32 v93, s38, v120
	ds_write_b32 v93, v91 offset:43008
	v_cndmask_b32_e64 v91, 0, 1, s[58:59]
	v_mul_f32_e32 v79, v125, v101
	v_mul_f32_e32 v81, v126, v104
	v_cmp_ne_u32_e64 s[26:27], 1, v91
	v_add_u32_e32 v101, s33, v120
	s_cbranch_vccnz .LBB0_1412
	v_mul_f32_e32 v91, v119, v81
	v_mul_f32_e32 v93, v118, v79
	v_cvt_pk_bf16_f32 v91, v93, v91
	ds_write_b32 v101, v91 offset:47360

.LBB0_1416:
	v_pk_add_f32 v[58:59], v[58:59], v[88:89]
	v_lshlrev_b32_e32 v121, 16, v9
	v_mul_f32_e32 v96, 0x3fb8aa3b, v58
	v_mul_f32_e32 v97, 0x3fb8aa3b, v59
	v_exp_f32_e32 v96, v96
	v_exp_f32_e32 v97, v97
	v_pk_add_f32 v[58:59], v[86:87], v[58:59] neg_lo:[0,1] neg_hi:[0,1]
	v_and_b32_e32 v122, 0xffff0000, v9
	v_mul_f32_e32 v58, 0x3fb8aa3b, v58
	v_rcp_f32_e32 v101, v96
	v_rcp_f32_e32 v104, v97
	v_exp_f32_e32 v123, v58
	v_mul_f32_e32 v58, 0x3fb8aa3b, v59
	v_exp_f32_e32 v124, v58
	v_mul_f32_e32 v58, v96, v121
	v_mul_f32_e32 v59, v97, v122
	v_cvt_pk_bf16_f32 v96, v58, v59
	v_lshl_add_u32 v97, s5, 1, v120
	ds_write_b32 v97, v96 offset:8192
	v_mul_f32_e32 v96, v80, v58
	v_mul_f32_e32 v121, v78, v59
	v_cvt_pk_bf16_f32 v96, v96, v121
	v_mul_f32_e32 v58, v90, v58
	v_mul_f32_e32 v59, v92, v59
	v_min_f32_e32 v101, 0x79297b5a, v101
	v_min_f32_e32 v104, 0x79297b5a, v104
	ds_write_b32 v97, v96 offset:25600
	v_cvt_pk_bf16_f32 v96, v58, v59

	global_store_dword v62, v96, s[0:1]
	v_mul_f32_e32 v96, v101, v102
	v_mul_f32_e32 v97, v104, v105
	v_cvt_pk_bf16_f32 v96, v96, v97
	v_add_u32_e32 v97, s50, v120
	v_mul_f32_e32 v58, v123, v102
	v_mul_f32_e32 v59, v124, v105
	ds_write_b32 v97, v96 offset:43008
	s_and_b64 vcc, exec, s[26:27]
	v_add_u32_e32 v96, s49, v120
	s_cbranch_vccz .LBB0_1451
	s_and_b64 vcc, exec, s[28:29]
	s_cbranch_vccz .LBB0_1452

.LBB0_1420:
	v_pk_add_f32 v[60:61], v[60:61], v[88:89]
	v_lshlrev_b32_e32 v104, 16, v10
	v_mul_f32_e32 v96, 0x3fb8aa3b, v60
	v_mul_f32_e32 v97, 0x3fb8aa3b, v61
	v_exp_f32_e32 v96, v96
	v_exp_f32_e32 v97, v97
	v_pk_add_f32 v[60:61], v[86:87], v[60:61] neg_lo:[0,1] neg_hi:[0,1]
	v_and_b32_e32 v105, 0xffff0000, v10
	v_mul_f32_e32 v60, 0x3fb8aa3b, v60
	v_rcp_f32_e32 v101, v96
	v_rcp_f32_e32 v102, v97
	v_exp_f32_e32 v121, v60
	v_mul_f32_e32 v60, 0x3fb8aa3b, v61
	v_exp_f32_e32 v122, v60
	v_mul_f32_e32 v60, v96, v104
	v_mul_f32_e32 v61, v97, v105
	v_cvt_pk_bf16_f32 v96, v60, v61
	v_lshl_add_u32 v97, s83, 1, v120
	ds_write_b32 v97, v96 offset:8192
	v_mul_f32_e32 v96, v80, v60
	v_mul_f32_e32 v104, v78, v61
	v_cvt_pk_bf16_f32 v96, v96, v104
	v_mul_f32_e32 v60, v90, v60
	v_mul_f32_e32 v61, v92, v61
	v_min_f32_e32 v101, 0x79297b5a, v101
	v_min_f32_e32 v102, 0x79297b5a, v102
	ds_write_b32 v97, v96 offset:25600
	v_cvt_pk_bf16_f32 v96, v60, v61

	global_store_dword v62, v96, s[78:79]
	v_mul_f32_e32 v96, v101, v103
	v_mul_f32_e32 v97, v102, v107
	v_cvt_pk_bf16_f32 v96, v96, v97
	v_add_u32_e32 v97, s51, v120
	v_mul_f32_e32 v60, v121, v103
	v_mul_f32_e32 v61, v122, v107
	ds_write_b32 v97, v96 offset:43008
	s_and_b64 vcc, exec, s[26:27]
	v_add_u32_e32 v96, s91, v120
	s_cbranch_vccz .LBB0_1453
	s_and_b64 vcc, exec, s[28:29]
	s_cbranch_vccz .LBB0_1454

.LBB0_1424:
	v_pk_add_f32 v[66:67], v[66:67], v[88:89]
	v_lshlrev_b32_e32 v103, 16, v11
	v_mul_f32_e32 v96, 0x3fb8aa3b, v66
	v_mul_f32_e32 v97, 0x3fb8aa3b, v67
	v_exp_f32_e32 v96, v96
	v_exp_f32_e32 v97, v97
	v_pk_add_f32 v[66:67], v[86:87], v[66:67] neg_lo:[0,1] neg_hi:[0,1]
	v_and_b32_e32 v104, 0xffff0000, v11
	v_mul_f32_e32 v66, 0x3fb8aa3b, v66
	v_rcp_f32_e32 v101, v96
	v_rcp_f32_e32 v102, v97
	v_exp_f32_e32 v105, v66
	v_mul_f32_e32 v66, 0x3fb8aa3b, v67
	v_exp_f32_e32 v107, v66
	v_mul_f32_e32 v66, v96, v103
	v_mul_f32_e32 v67, v97, v104
	v_cvt_pk_bf16_f32 v96, v66, v67
	v_lshl_add_u32 v97, s97, 1, v120
	ds_write_b32 v97, v96 offset:8192
	v_mul_f32_e32 v96, v80, v66
	v_mul_f32_e32 v103, v78, v67
	v_cvt_pk_bf16_f32 v96, v96, v103
	v_mul_f32_e32 v66, v90, v66
	v_mul_f32_e32 v67, v92, v67
	v_min_f32_e32 v101, 0x79297b5a, v101
	v_min_f32_e32 v102, 0x79297b5a, v102
	ds_write_b32 v97, v96 offset:25600
	v_cvt_pk_bf16_f32 v96, v66, v67

	global_store_dword v62, v96, s[68:69]
	v_mul_f32_e32 v96, v101, v106
	v_mul_f32_e32 v97, v102, v109
	v_cvt_pk_bf16_f32 v96, v96, v97
	v_add_u32_e32 v97, s89, v120
	v_mul_f32_e32 v66, v105, v106
	v_mul_f32_e32 v67, v107, v109
	ds_write_b32 v97, v96 offset:43008
	s_and_b64 vcc, exec, s[26:27]
	v_add_u32_e32 v96, s48, v120
	s_cbranch_vccz .LBB0_1455
	s_and_b64 vcc, exec, s[28:29]
	s_cbranch_vccz .LBB0_1456

.LBB0_1428:
	v_pk_add_f32 v[68:69], v[68:69], v[88:89]
	v_lshlrev_b32_e32 v103, 16, v12
	v_mul_f32_e32 v96, 0x3fb8aa3b, v68
	v_mul_f32_e32 v97, 0x3fb8aa3b, v69
	v_exp_f32_e32 v96, v96
	v_exp_f32_e32 v97, v97
	v_pk_add_f32 v[68:69], v[86:87], v[68:69] neg_lo:[0,1] neg_hi:[0,1]
	v_and_b32_e32 v104, 0xffff0000, v12
	v_mul_f32_e32 v68, 0x3fb8aa3b, v68
	v_rcp_f32_e32 v101, v96
	v_rcp_f32_e32 v102, v97
	v_exp_f32_e32 v105, v68
	v_mul_f32_e32 v68, 0x3fb8aa3b, v69
	v_exp_f32_e32 v106, v68
	v_mul_f32_e32 v68, v96, v103
	v_mul_f32_e32 v69, v97, v104
	v_cvt_pk_bf16_f32 v96, v68, v69
	v_lshl_add_u32 v97, s57, 1, v120
	ds_write_b32 v97, v96 offset:8192
	v_mul_f32_e32 v96, v80, v68
	v_mul_f32_e32 v103, v78, v69
	v_cvt_pk_bf16_f32 v96, v96, v103
	v_mul_f32_e32 v68, v90, v68
	v_mul_f32_e32 v69, v92, v69
	v_min_f32_e32 v101, 0x79297b5a, v101
	v_min_f32_e32 v102, 0x79297b5a, v102
	ds_write_b32 v97, v96 offset:25600
	v_cvt_pk_bf16_f32 v96, v68, v69

	global_store_dword v62, v96, s[42:43]
	v_mul_f32_e32 v96, v101, v108
	v_mul_f32_e32 v97, v102, v112
	v_cvt_pk_bf16_f32 v96, v96, v97
	v_add_u32_e32 v97, s66, v120
	v_mul_f32_e32 v68, v105, v108
	v_mul_f32_e32 v69, v106, v112
	ds_write_b32 v97, v96 offset:43008
	s_and_b64 vcc, exec, s[26:27]
	v_add_u32_e32 v96, s96, v120
	s_cbranch_vccz .LBB0_1457
	s_and_b64 vcc, exec, s[28:29]
	s_cbranch_vccz .LBB0_1458

.LBB0_1432:
	v_pk_add_f32 v[70:71], v[70:71], v[88:89]
	v_lshlrev_b32_e32 v103, 16, v13
	v_mul_f32_e32 v96, 0x3fb8aa3b, v70
	v_mul_f32_e32 v97, 0x3fb8aa3b, v71
	v_exp_f32_e32 v96, v96
	v_exp_f32_e32 v97, v97
	v_pk_add_f32 v[70:71], v[86:87], v[70:71] neg_lo:[0,1] neg_hi:[0,1]
	v_and_b32_e32 v104, 0xffff0000, v13
	v_mul_f32_e32 v70, 0x3fb8aa3b, v70
	v_rcp_f32_e32 v101, v96
	v_rcp_f32_e32 v102, v97
	v_exp_f32_e32 v105, v70
	v_mul_f32_e32 v70, 0x3fb8aa3b, v71
	v_exp_f32_e32 v106, v70
	v_mul_f32_e32 v70, v96, v103
	v_mul_f32_e32 v71, v97, v104
	v_cvt_pk_bf16_f32 v96, v70, v71
	v_lshl_add_u32 v97, s46, 1, v120
	ds_write_b32 v97, v96 offset:8192
	v_mul_f32_e32 v96, v80, v70
	v_mul_f32_e32 v103, v78, v71
	v_cvt_pk_bf16_f32 v96, v96, v103
	v_mul_f32_e32 v70, v90, v70
	v_mul_f32_e32 v71, v92, v71
	v_min_f32_e32 v101, 0x79297b5a, v101
	v_min_f32_e32 v102, 0x79297b5a, v102
	ds_write_b32 v97, v96 offset:25600
	v_cvt_pk_bf16_f32 v96, v70, v71

	global_store_dword v62, v96, s[94:95]
	v_mul_f32_e32 v96, v101, v110
	v_mul_f32_e32 v97, v102, v114
	v_cvt_pk_bf16_f32 v96, v96, v97
	v_add_u32_e32 v97, s67, v120
	v_mul_f32_e32 v70, v105, v110
	v_mul_f32_e32 v71, v106, v114
	ds_write_b32 v97, v96 offset:43008
	s_and_b64 vcc, exec, s[26:27]
	v_add_u32_e32 v96, s4, v120
	s_cbranch_vccz .LBB0_1459
	s_and_b64 vcc, exec, s[28:29]
	s_cbranch_vccz .LBB0_1460

.LBB0_1436:
	v_pk_add_f32 v[72:73], v[88:89], v[72:73]
	v_lshlrev_b32_e32 v103, 16, v14
	v_mul_f32_e32 v96, 0x3fb8aa3b, v72
	v_mul_f32_e32 v97, 0x3fb8aa3b, v73
	v_exp_f32_e32 v96, v96
	v_exp_f32_e32 v97, v97
	v_pk_add_f32 v[72:73], v[86:87], v[72:73] neg_lo:[0,1] neg_hi:[0,1]
	v_and_b32_e32 v104, 0xffff0000, v14
	v_mul_f32_e32 v72, 0x3fb8aa3b, v72
	v_rcp_f32_e32 v101, v96
	v_rcp_f32_e32 v102, v97
	v_exp_f32_e32 v105, v72
	v_mul_f32_e32 v72, 0x3fb8aa3b, v73
	v_exp_f32_e32 v106, v72
	v_mul_f32_e32 v72, v96, v103
	v_mul_f32_e32 v73, v97, v104
	v_cvt_pk_bf16_f32 v96, v72, v73
	v_lshl_add_u32 v97, s47, 1, v120
	ds_write_b32 v97, v96 offset:8192
	v_mul_f32_e32 v96, v80, v72
	v_mul_f32_e32 v103, v78, v73
	v_cvt_pk_bf16_f32 v96, v96, v103
	v_mul_f32_e32 v72, v90, v72
	v_mul_f32_e32 v73, v92, v73
	v_min_f32_e32 v101, 0x79297b5a, v101
	v_min_f32_e32 v102, 0x79297b5a, v102
	ds_write_b32 v97, v96 offset:25600
	v_cvt_pk_bf16_f32 v96, v72, v73

	global_store_dword v62, v96, s[44:45]
	v_mul_f32_e32 v96, v101, v113
	v_mul_f32_e32 v97, v102, v116
	v_cvt_pk_bf16_f32 v96, v96, v97
	v_add_u32_e32 v97, s87, v120
	v_mul_f32_e32 v72, v105, v113
	v_mul_f32_e32 v73, v106, v116
	ds_write_b32 v97, v96 offset:43008
	s_and_b64 vcc, exec, s[26:27]
	v_add_u32_e32 v96, s40, v120
	s_cbranch_vccz .LBB0_1461
	s_and_b64 vcc, exec, s[28:29]
	s_cbranch_vccz .LBB0_1462

.LBB0_1440:
	v_pk_add_f32 v[74:75], v[88:89], v[74:75]
	v_and_b32_e32 v102, 0xffff0000, v15
	v_mul_f32_e32 v88, 0x3fb8aa3b, v74
	v_mul_f32_e32 v89, 0x3fb8aa3b, v75
	v_exp_f32_e32 v88, v88
	v_exp_f32_e32 v89, v89
	v_pk_add_f32 v[74:75], v[86:87], v[74:75] neg_lo:[0,1] neg_hi:[0,1]
	v_lshlrev_b32_e32 v101, 16, v15
	v_rcp_f32_e32 v96, v88
	v_rcp_f32_e32 v97, v89
	v_mul_f32_e32 v74, 0x3fb8aa3b, v74
	v_exp_f32_e32 v86, v74
	v_mul_f32_e32 v74, 0x3fb8aa3b, v75
	v_mul_f32_e32 v75, v89, v102
	v_exp_f32_e32 v87, v74
	v_mul_f32_e32 v74, v88, v101
	v_lshl_add_u32 v89, s41, 1, v120
	v_mul_f32_e32 v78, v78, v75
	v_cvt_pk_bf16_f32 v88, v74, v75
	ds_write_b32 v89, v88 offset:8192
	v_mul_f32_e32 v80, v80, v74
	v_cvt_pk_bf16_f32 v78, v80, v78
	v_mul_f32_e32 v74, v90, v74
	v_mul_f32_e32 v75, v92, v75
	v_min_f32_e32 v96, 0x79297b5a, v96
	v_min_f32_e32 v97, 0x79297b5a, v97
	ds_write_b32 v89, v78 offset:25600
	v_cvt_pk_bf16_f32 v78, v74, v75

	global_store_dword v62, v78, s[92:93]
	v_mul_f32_e32 v78, v96, v115
	v_mul_f32_e32 v80, v97, v117
	v_cvt_pk_bf16_f32 v78, v78, v80
	v_add_u32_e32 v80, s72, v120
	v_mul_f32_e32 v74, v86, v115
	v_mul_f32_e32 v75, v87, v117
	ds_write_b32 v80, v78 offset:43008
	s_and_b64 vcc, exec, s[26:27]
	v_add_u32_e32 v78, s90, v120
	s_cbranch_vccz .LBB0_1463
	s_and_b64 vcc, exec, s[28:29]
	s_cbranch_vccz .LBB0_1464

.LBB0_1449:
	s_andn2_b64 vcc, exec, s[2:3]
	s_cbranch_vccnz .LBB0_1465
	v_readlane_b32 s2, v255, 41
	v_readlane_b32 s3, v255, 42
	v_readlane_b32 vcc_lo, v255, 43
	v_readlane_b32 vcc_hi, v255, 44
	v_readlane_b32 s26, v255, 45
	v_readlane_b32 s27, v255, 46
	s_nop 0
	global_load_dword v8, v62, s[2:3]
	v_readlane_b32 s2, v255, 33
	v_readlane_b32 s3, v255, 34
	global_load_dword v16, v62, vcc
	v_readlane_b32 vcc_lo, v255, 35
	v_readlane_b32 vcc_hi, v255, 36
	global_load_dword v2, v62, s[26:27]
	v_readlane_b32 s26, v255, 37
	v_readlane_b32 s27, v255, 38
	global_load_dword v9, v62, s[2:3]
	v_readlane_b32 s2, v255, 27
	v_readlane_b32 s3, v255, 28
	global_load_dword v17, v62, vcc
	v_readlane_b32 vcc_lo, v255, 29
	v_readlane_b32 vcc_hi, v255, 30
	global_load_dword v3, v62, s[26:27]
	v_readlane_b32 s26, v255, 31
	v_readlane_b32 s27, v255, 32
	global_load_dword v10, v62, s[2:3]
	v_readlane_b32 s2, v255, 21
	v_readlane_b32 s3, v255, 22
	global_load_dword v18, v62, vcc
	v_readlane_b32 vcc_lo, v255, 23
	v_readlane_b32 vcc_hi, v255, 24
	global_load_dword v4, v62, s[26:27]
	v_readlane_b32 s26, v255, 25
	v_readlane_b32 s27, v255, 26
	global_load_dword v11, v62, s[2:3]
	v_readlane_b32 s2, v255, 15
	v_readlane_b32 s3, v255, 16
	global_load_dword v19, v62, vcc
	v_readlane_b32 vcc_lo, v255, 17
	v_readlane_b32 vcc_hi, v255, 18
	global_load_dword v5, v62, s[26:27]
	v_readlane_b32 s26, v255, 19
	v_readlane_b32 s27, v255, 20
	global_load_dword v12, v62, s[2:3]
	v_readlane_b32 s2, v255, 9
	v_readlane_b32 s3, v255, 10
	global_load_dword v20, v62, vcc
	v_readlane_b32 vcc_lo, v255, 11
	v_readlane_b32 vcc_hi, v255, 12
	global_load_dword v6, v62, s[26:27]
	v_readlane_b32 s26, v255, 13
	v_readlane_b32 s27, v255, 14
	global_load_dword v13, v62, s[2:3]
	v_readlane_b32 s2, v255, 3
	v_readlane_b32 s3, v255, 4
	global_load_dword v21, v62, vcc
	v_readlane_b32 vcc_lo, v255, 5
	v_readlane_b32 vcc_hi, v255, 6
	global_load_dword v7, v62, s[26:27]
	v_readlane_b32 s26, v255, 7
	v_readlane_b32 s27, v255, 8
	global_load_dword v14, v62, s[2:3]
	v_readlane_b32 s2, v254, 61
	v_readlane_b32 s3, v254, 62
	global_load_dword v22, v62, vcc
	v_readlane_b32 vcc_lo, v254, 63
	v_readlane_b32 vcc_hi, v255, 0
	global_load_dword v24, v62, s[26:27]
	v_readlane_b32 s26, v255, 1
	v_readlane_b32 s27, v255, 2
	global_load_dword v15, v62, s[2:3]
	s_nop 0
	global_load_dword v23, v62, vcc
	s_nop 1
	global_load_dword v25, v62, s[26:27]
	s_branch .LBB0_1466
